# beta/alpha MFMA GEMV: weight-piece loads issued before the entry barrier, two alternating f32 accumulators summed in the epilogue
# baseline (speedup 1.0000x reference)
; __device__ __forceinline__ int ptid_(int wave) { int l_; asm volatile("v_mbcnt_lo_u32_b32 %0, -1, 0\n\tv_mbcnt_hi_u32_b32 %0, -1, %0" : "=v"(l_)); return (wave << 6) | l_; }
; __device__ void ba_item(const Params& p, int L, int rp) {
;   const float* misc = (const float*)(p.ws + MISC_OFF);
;   float* miscw = (float*)(p.ws + MISC_OFF);
;   const bfu* hb = (const bfu*)(p.ws + HB_OFF);
;   const float* wba = misc + MF_WBA + (L >> 1) * 8192;
;   const float* rowss = misc + MF_RSP + (L == 0 ? 0L : 2L * MTOK * 16);
;   int tid = ptid_(p.tid); asm volatile("" : "+v"(tid));
;   const int wid = tid >> 6, lane = tid & 63;
;   f32x4 wr_[8][4];
;   _Pragma("unroll") for (int j = 0; j < 8; ++j) _Pragma("unroll") for (int e4 = 0; e4 < 4; ++e4)
;     wr_[j][e4] = *(const f32x4*)(wba + j * 1024 + lane * 16 + e4 * 4);
;   for (int bt = 0; bt < 8; ++bt) {
;     bf16x8 h0[2], h1[2]; f32x4 ps[2][4];
;     _Pragma("unroll") for (int u = 0; u < 2; ++u) {
;       const int row = rp * 128 + wid * 16 + bt * 2 + u;
;       const bfu* hr = hb + (long)row * 1024 + lane * 16;
;       h0[u] = *(const bf16x8*)hr; h1[u] = *(const bf16x8*)(hr + 8);
;       _Pragma("unroll") for (int i = 0; i < 4; ++i) ps[u][i] = *(const f32x4*)(rowss + (long)row * 16 + i * 4);
.LBB0_612:
	s_cmpk_gt_i32 s18, 0x6ff
	s_mov_b64 s[0:1], -1
	s_cbranch_scc0 .LBB0_628
	v_mbcnt_lo_u32_b32 v0, -1, 0
	v_mbcnt_hi_u32_b32 v0, -1, v0
	s_waitcnt vmcnt(0) lgkmcnt(0)
	v_or_b32_e32 v144, s33, v0
	v_lshlrev_b32_e32 v150, 4, v144
	global_load_dwordx4 v[152:155], v150, s[26:27]
	v_add_u32_e32 v150, 0x2000, v150
	global_load_dwordx4 v[156:159], v150, s[26:27]
	v_add_u32_e32 v150, 0x2000, v150
	global_load_dwordx4 v[160:163], v150, s[26:27]
	v_add_u32_e32 v150, 0x2000, v150
	global_load_dwordx4 v[164:167], v150, s[26:27]
	s_barrier
	v_readlane_b32 s24, v254, 62
	v_readlane_b32 s25, v254, 63
	s_lshr_b32 s2, s33, 2
	s_add_i32 s2, s2, s20
	s_add_i32 s2, s2, 0xfffc8000
	v_and_b32_e32 v2, 15, v0
	v_lshrrev_b32_e32 v3, 4, v0
	v_and_b32_e32 v145, 0xff, v144
	v_lshrrev_b32_e32 v149, 3, v145
	v_lshlrev_b32_e32 v149, 10, v149
	v_bfe_u32 v146, v144, 1, 2
	v_lshl_or_b32 v149, v146, 8, v149
	v_lshrrev_b32_e32 v146, 8, v144
	v_lshl_or_b32 v149, v146, 5, v149
	v_and_b32_e32 v146, 1, v144
	v_lshl_or_b32 v149, v146, 4, v149
	v_add_u32_e32 v144, s2, v2
	v_lshlrev_b32_e32 v144, 11, v144
	v_lshl_add_u32 v144, v3, 4, v144
	v_mov_b32_e32 v145, 0
	v_lshl_add_u64 v[4:5], s[80:81], 0, v[144:145]
	v_and_b32_e32 v138, 7, v2
	v_lshlrev_b32_e32 v148, 5, v138
	v_lshl_or_b32 v148, v3, 8, v148
	v_lshl_add_u32 v144, v3, 2, s2
	v_lshlrev_b32_e32 v144, 6, v144
	v_lshl_add_u64 v[136:137], s[24:25], 0, v[144:145]
	v_max_u32_e32 v144, 4, v138
	v_add_u32_e32 v144, s19, v144
	v_lshlrev_b32_e32 v144, 2, v144
	v_readlane_b32 s92, v254, 0
	v_readlane_b32 s93, v254, 1
	v_readlane_b32 s94, v254, 2
	v_readlane_b32 s95, v254, 3
	v_readlane_b32 s0, v252, 18
	v_readlane_b32 s1, v252, 19
	v_lshl_add_u32 v146, v3, 2, s2
	v_lshlrev_b32_e32 v146, 5, v146
	v_lshl_add_u32 v146, v138, 2, v146
	v_mov_b32_e32 v147, 0
	v_lshl_add_u64 v[140:141], s[0:1], 0, v[146:147]
	global_load_dword v142, v144, s[94:95]
	global_load_dword v143, v144, s[92:93]
	global_load_dwordx4 v[72:75], v[136:137], off offset:0
	global_load_dwordx4 v[76:79], v[136:137], off offset:16
	global_load_dwordx4 v[80:83], v[136:137], off offset:32
	global_load_dwordx4 v[84:87], v[136:137], off offset:48
	global_load_dwordx4 v[88:91], v[136:137], off offset:64
	global_load_dwordx4 v[92:95], v[136:137], off offset:80
	global_load_dwordx4 v[96:99], v[136:137], off offset:96
	global_load_dwordx4 v[100:103], v[136:137], off offset:112
	global_load_dwordx4 v[104:107], v[136:137], off offset:128
	global_load_dwordx4 v[108:111], v[136:137], off offset:144
	global_load_dwordx4 v[112:115], v[136:137], off offset:160
	global_load_dwordx4 v[116:119], v[136:137], off offset:176
	global_load_dwordx4 v[120:123], v[136:137], off offset:192
	global_load_dwordx4 v[124:127], v[136:137], off offset:208
	global_load_dwordx4 v[128:131], v[136:137], off offset:224
	global_load_dwordx4 v[132:135], v[136:137], off offset:240
	v_mov_b32_e32 v8, 0
	v_mov_b32_e32 v9, 0
	v_mov_b32_e32 v10, 0
	v_mov_b32_e32 v11, 0
	v_mov_b32_e32 v12, 0
	v_mov_b32_e32 v13, 0
	v_mov_b32_e32 v14, 0
	v_mov_b32_e32 v15, 0
	global_load_dwordx4 v[16:19], v[4:5], off
	global_load_dwordx4 v[20:23], v[4:5], off offset:64
	global_load_dwordx4 v[24:27], v[4:5], off offset:128
	global_load_dwordx4 v[28:31], v[4:5], off offset:192
	global_load_dwordx4 v[32:35], v[4:5], off offset:256
	global_load_dwordx4 v[36:39], v[4:5], off offset:320
	global_load_dwordx4 v[40:43], v[4:5], off offset:384
	global_load_dwordx4 v[44:47], v[4:5], off offset:448
	s_waitcnt vmcnt(26)
	ds_write_b128 v149, v[152:155]
	ds_write_b128 v149, v[156:159] offset:64
	ds_write_b128 v149, v[160:163] offset:128
	ds_write_b128 v149, v[164:167] offset:192
	s_waitcnt lgkmcnt(0)
	s_barrier
	ds_read_b128 v[48:51], v148
	ds_read_b128 v[52:55], v148 offset:16
	ds_read_b128 v[56:59], v148 offset:1024
	ds_read_b128 v[60:63], v148 offset:1040
	s_waitcnt vmcnt(7)
	v_lshlrev_b32_e32 v64, 16, v16
	v_and_b32_e32 v65, 0xffff0000, v16
	v_lshlrev_b32_e32 v66, 16, v17
	v_and_b32_e32 v67, 0xffff0000, v17
	v_lshlrev_b32_e32 v68, 16, v18
	v_and_b32_e32 v69, 0xffff0000, v18
	v_lshlrev_b32_e32 v70, 16, v19
	v_and_b32_e32 v71, 0xffff0000, v19
	s_waitcnt lgkmcnt(2)
	v_mfma_f32_16x16x4_f32 v[8:11], v64, v48, v[8:11]
	v_mfma_f32_16x16x4_f32 v[12:15], v65, v49, v[12:15]
	v_mfma_f32_16x16x4_f32 v[8:11], v66, v50, v[8:11]
	v_mfma_f32_16x16x4_f32 v[12:15], v67, v51, v[12:15]
	v_mfma_f32_16x16x4_f32 v[8:11], v68, v52, v[8:11]
	v_mfma_f32_16x16x4_f32 v[12:15], v69, v53, v[12:15]
	v_mfma_f32_16x16x4_f32 v[8:11], v70, v54, v[8:11]
	v_mfma_f32_16x16x4_f32 v[12:15], v71, v55, v[12:15]
	global_load_dwordx4 v[16:19], v[4:5], off offset:512
	ds_read_b128 v[48:51], v148 offset:2048
	ds_read_b128 v[52:55], v148 offset:2064
	s_waitcnt vmcnt(7)
	v_lshlrev_b32_e32 v64, 16, v20
	v_and_b32_e32 v65, 0xffff0000, v20
	v_lshlrev_b32_e32 v66, 16, v21
	v_and_b32_e32 v67, 0xffff0000, v21
	v_lshlrev_b32_e32 v68, 16, v22
	v_and_b32_e32 v69, 0xffff0000, v22
	v_lshlrev_b32_e32 v70, 16, v23
	v_and_b32_e32 v71, 0xffff0000, v23
	s_waitcnt lgkmcnt(2)
	v_mfma_f32_16x16x4_f32 v[8:11], v64, v56, v[8:11]
	v_mfma_f32_16x16x4_f32 v[12:15], v65, v57, v[12:15]
	v_mfma_f32_16x16x4_f32 v[8:11], v66, v58, v[8:11]
	v_mfma_f32_16x16x4_f32 v[12:15], v67, v59, v[12:15]
	v_mfma_f32_16x16x4_f32 v[8:11], v68, v60, v[8:11]
	v_mfma_f32_16x16x4_f32 v[12:15], v69, v61, v[12:15]
	v_mfma_f32_16x16x4_f32 v[8:11], v70, v62, v[8:11]
	v_mfma_f32_16x16x4_f32 v[12:15], v71, v63, v[12:15]
	global_load_dwordx4 v[20:23], v[4:5], off offset:576
	ds_read_b128 v[56:59], v148 offset:3072
	ds_read_b128 v[60:63], v148 offset:3088
	s_waitcnt vmcnt(7)
; __device__ __forceinline__ float bf2f(bfu h) { return __uint_as_float(((unsigned)h) << 16); }
; #define SHX(v, m) shx_((v), (m), lane)
; __device__ void ba_item(const Params& p, int L, int rp) {
;     ...
;       _Pragma("unroll") for (int e = 0; e < 8; ++e) { hf[e] = bf2f((bfu)h0[u][e]); hf[8 + e] = bf2f((bfu)h1[u][e]); }
;       float a[8];
;       _Pragma("unroll") for (int j = 0; j < 8; ++j) {
;         float s = 0.f;
;         _Pragma("unroll") for (int e4 = 0; e4 < 4; ++e4) _Pragma("unroll") for (int e = 0; e < 4; ++e) s += hf[e4 * 4 + e] * wr_[j][e4][e];
;         _Pragma("unroll") for (int o = 32; o >= 1; o >>= 1) s += SHX(s, o);
;         a[j] = s;
;       }
	v_lshlrev_b32_e32 v64, 16, v24
	v_and_b32_e32 v65, 0xffff0000, v24
	v_lshlrev_b32_e32 v66, 16, v25
	v_and_b32_e32 v67, 0xffff0000, v25
	v_lshlrev_b32_e32 v68, 16, v26
	v_and_b32_e32 v69, 0xffff0000, v26
	v_lshlrev_b32_e32 v70, 16, v27
	v_and_b32_e32 v71, 0xffff0000, v27
	s_waitcnt lgkmcnt(2)
	v_mfma_f32_16x16x4_f32 v[8:11], v64, v48, v[8:11]
	v_mfma_f32_16x16x4_f32 v[12:15], v65, v49, v[12:15]
	v_mfma_f32_16x16x4_f32 v[8:11], v66, v50, v[8:11]
	v_mfma_f32_16x16x4_f32 v[12:15], v67, v51, v[12:15]
	v_mfma_f32_16x16x4_f32 v[8:11], v68, v52, v[8:11]
	v_mfma_f32_16x16x4_f32 v[12:15], v69, v53, v[12:15]
	v_mfma_f32_16x16x4_f32 v[8:11], v70, v54, v[8:11]
	v_mfma_f32_16x16x4_f32 v[12:15], v71, v55, v[12:15]
	global_load_dwordx4 v[24:27], v[4:5], off offset:640
	ds_read_b128 v[48:51], v148 offset:4096
	ds_read_b128 v[52:55], v148 offset:4112
	s_waitcnt vmcnt(7)
	v_lshlrev_b32_e32 v64, 16, v28
	v_and_b32_e32 v65, 0xffff0000, v28
	v_lshlrev_b32_e32 v66, 16, v29
	v_and_b32_e32 v67, 0xffff0000, v29
	v_lshlrev_b32_e32 v68, 16, v30
	v_and_b32_e32 v69, 0xffff0000, v30
	v_lshlrev_b32_e32 v70, 16, v31
	v_and_b32_e32 v71, 0xffff0000, v31
	s_waitcnt lgkmcnt(2)
	v_mfma_f32_16x16x4_f32 v[8:11], v64, v56, v[8:11]
	v_mfma_f32_16x16x4_f32 v[12:15], v65, v57, v[12:15]
	v_mfma_f32_16x16x4_f32 v[8:11], v66, v58, v[8:11]
	v_mfma_f32_16x16x4_f32 v[12:15], v67, v59, v[12:15]
	v_mfma_f32_16x16x4_f32 v[8:11], v68, v60, v[8:11]
	v_mfma_f32_16x16x4_f32 v[12:15], v69, v61, v[12:15]
	v_mfma_f32_16x16x4_f32 v[8:11], v70, v62, v[8:11]
	v_mfma_f32_16x16x4_f32 v[12:15], v71, v63, v[12:15]
	global_load_dwordx4 v[28:31], v[4:5], off offset:704
	ds_read_b128 v[56:59], v148 offset:5120
	ds_read_b128 v[60:63], v148 offset:5136
	s_waitcnt vmcnt(7)
	v_lshlrev_b32_e32 v64, 16, v32
	v_and_b32_e32 v65, 0xffff0000, v32
	v_lshlrev_b32_e32 v66, 16, v33
	v_and_b32_e32 v67, 0xffff0000, v33
	v_lshlrev_b32_e32 v68, 16, v34
	v_and_b32_e32 v69, 0xffff0000, v34
	v_lshlrev_b32_e32 v70, 16, v35
	v_and_b32_e32 v71, 0xffff0000, v35
	s_waitcnt lgkmcnt(2)
	v_mfma_f32_16x16x4_f32 v[8:11], v64, v48, v[8:11]
	v_mfma_f32_16x16x4_f32 v[12:15], v65, v49, v[12:15]
	v_mfma_f32_16x16x4_f32 v[8:11], v66, v50, v[8:11]
	v_mfma_f32_16x16x4_f32 v[12:15], v67, v51, v[12:15]
	v_mfma_f32_16x16x4_f32 v[8:11], v68, v52, v[8:11]
	v_mfma_f32_16x16x4_f32 v[12:15], v69, v53, v[12:15]
	v_mfma_f32_16x16x4_f32 v[8:11], v70, v54, v[8:11]
	v_mfma_f32_16x16x4_f32 v[12:15], v71, v55, v[12:15]
	global_load_dwordx4 v[32:35], v[4:5], off offset:768
	ds_read_b128 v[48:51], v148 offset:6144
	ds_read_b128 v[52:55], v148 offset:6160
	s_waitcnt vmcnt(7)
	v_lshlrev_b32_e32 v64, 16, v36
	v_and_b32_e32 v65, 0xffff0000, v36
	v_lshlrev_b32_e32 v66, 16, v37
	v_and_b32_e32 v67, 0xffff0000, v37
	v_lshlrev_b32_e32 v68, 16, v38
	v_and_b32_e32 v69, 0xffff0000, v38
	v_lshlrev_b32_e32 v70, 16, v39
	v_and_b32_e32 v71, 0xffff0000, v39
	s_waitcnt lgkmcnt(2)
	v_mfma_f32_16x16x4_f32 v[8:11], v64, v56, v[8:11]
	v_mfma_f32_16x16x4_f32 v[12:15], v65, v57, v[12:15]
	v_mfma_f32_16x16x4_f32 v[8:11], v66, v58, v[8:11]
	v_mfma_f32_16x16x4_f32 v[12:15], v67, v59, v[12:15]
	v_mfma_f32_16x16x4_f32 v[8:11], v68, v60, v[8:11]
	v_mfma_f32_16x16x4_f32 v[12:15], v69, v61, v[12:15]
	v_mfma_f32_16x16x4_f32 v[8:11], v70, v62, v[8:11]
	v_mfma_f32_16x16x4_f32 v[12:15], v71, v63, v[12:15]
	global_load_dwordx4 v[36:39], v[4:5], off offset:832
	ds_read_b128 v[56:59], v148 offset:7168
	ds_read_b128 v[60:63], v148 offset:7184
	s_waitcnt vmcnt(7)
	v_lshlrev_b32_e32 v64, 16, v40
	v_and_b32_e32 v65, 0xffff0000, v40
	v_lshlrev_b32_e32 v66, 16, v41
	v_and_b32_e32 v67, 0xffff0000, v41
	v_lshlrev_b32_e32 v68, 16, v42
	v_and_b32_e32 v69, 0xffff0000, v42
	v_lshlrev_b32_e32 v70, 16, v43
	v_and_b32_e32 v71, 0xffff0000, v43
	s_waitcnt lgkmcnt(2)
	v_mfma_f32_16x16x4_f32 v[8:11], v64, v48, v[8:11]
	v_mfma_f32_16x16x4_f32 v[12:15], v65, v49, v[12:15]
	v_mfma_f32_16x16x4_f32 v[8:11], v66, v50, v[8:11]
	v_mfma_f32_16x16x4_f32 v[12:15], v67, v51, v[12:15]
	v_mfma_f32_16x16x4_f32 v[8:11], v68, v52, v[8:11]
	v_mfma_f32_16x16x4_f32 v[12:15], v69, v53, v[12:15]
	v_mfma_f32_16x16x4_f32 v[8:11], v70, v54, v[8:11]
	v_mfma_f32_16x16x4_f32 v[12:15], v71, v55, v[12:15]
	global_load_dwordx4 v[40:43], v[4:5], off offset:896
	ds_read_b128 v[48:51], v148 offset:8192
	ds_read_b128 v[52:55], v148 offset:8208
	s_waitcnt vmcnt(7)
	v_lshlrev_b32_e32 v64, 16, v44
	v_and_b32_e32 v65, 0xffff0000, v44
	v_lshlrev_b32_e32 v66, 16, v45
	v_and_b32_e32 v67, 0xffff0000, v45
	v_lshlrev_b32_e32 v68, 16, v46
	v_and_b32_e32 v69, 0xffff0000, v46
	v_lshlrev_b32_e32 v70, 16, v47
	v_and_b32_e32 v71, 0xffff0000, v47
	s_waitcnt lgkmcnt(2)
	v_mfma_f32_16x16x4_f32 v[8:11], v64, v56, v[8:11]
	v_mfma_f32_16x16x4_f32 v[12:15], v65, v57, v[12:15]
	v_mfma_f32_16x16x4_f32 v[8:11], v66, v58, v[8:11]
	v_mfma_f32_16x16x4_f32 v[12:15], v67, v59, v[12:15]
	v_mfma_f32_16x16x4_f32 v[8:11], v68, v60, v[8:11]
	v_mfma_f32_16x16x4_f32 v[12:15], v69, v61, v[12:15]
	v_mfma_f32_16x16x4_f32 v[8:11], v70, v62, v[8:11]
	v_mfma_f32_16x16x4_f32 v[12:15], v71, v63, v[12:15]
	global_load_dwordx4 v[44:47], v[4:5], off offset:960
	ds_read_b128 v[56:59], v148 offset:9216
	ds_read_b128 v[60:63], v148 offset:9232
	s_waitcnt vmcnt(7)
	v_lshlrev_b32_e32 v64, 16, v16
	v_and_b32_e32 v65, 0xffff0000, v16
	v_lshlrev_b32_e32 v66, 16, v17
	v_and_b32_e32 v67, 0xffff0000, v17
	v_lshlrev_b32_e32 v68, 16, v18
	v_and_b32_e32 v69, 0xffff0000, v18
	v_lshlrev_b32_e32 v70, 16, v19
	v_and_b32_e32 v71, 0xffff0000, v19
	s_waitcnt lgkmcnt(2)
; __device__ __forceinline__ float bf2f(bfu h) { return __uint_as_float(((unsigned)h) << 16); }
; #define SHX(v, m) shx_((v), (m), lane)
; __device__ void ba_item(const Params& p, int L, int rp) {
;     ...
;       _Pragma("unroll") for (int e = 0; e < 8; ++e) { hf[e] = bf2f((bfu)h0[u][e]); hf[8 + e] = bf2f((bfu)h1[u][e]); }
;       float a[8];
;       _Pragma("unroll") for (int j = 0; j < 8; ++j) {
;         float s = 0.f;
;         _Pragma("unroll") for (int e4 = 0; e4 < 4; ++e4) _Pragma("unroll") for (int e = 0; e < 4; ++e) s += hf[e4 * 4 + e] * wr_[j][e4][e];
;         _Pragma("unroll") for (int o = 32; o >= 1; o >>= 1) s += SHX(s, o);
;         a[j] = s;
;       }
	v_mfma_f32_16x16x4_f32 v[8:11], v64, v48, v[8:11]
	v_mfma_f32_16x16x4_f32 v[12:15], v65, v49, v[12:15]
	v_mfma_f32_16x16x4_f32 v[8:11], v66, v50, v[8:11]
	v_mfma_f32_16x16x4_f32 v[12:15], v67, v51, v[12:15]
	v_mfma_f32_16x16x4_f32 v[8:11], v68, v52, v[8:11]
	v_mfma_f32_16x16x4_f32 v[12:15], v69, v53, v[12:15]
	v_mfma_f32_16x16x4_f32 v[8:11], v70, v54, v[8:11]
	v_mfma_f32_16x16x4_f32 v[12:15], v71, v55, v[12:15]
	global_load_dwordx4 v[16:19], v[4:5], off offset:1024
	ds_read_b128 v[48:51], v148 offset:10240
	ds_read_b128 v[52:55], v148 offset:10256
	s_waitcnt vmcnt(7)
	v_lshlrev_b32_e32 v64, 16, v20
	v_and_b32_e32 v65, 0xffff0000, v20
	v_lshlrev_b32_e32 v66, 16, v21
	v_and_b32_e32 v67, 0xffff0000, v21
	v_lshlrev_b32_e32 v68, 16, v22
	v_and_b32_e32 v69, 0xffff0000, v22
	v_lshlrev_b32_e32 v70, 16, v23
	v_and_b32_e32 v71, 0xffff0000, v23
	s_waitcnt lgkmcnt(2)
	v_mfma_f32_16x16x4_f32 v[8:11], v64, v56, v[8:11]
	v_mfma_f32_16x16x4_f32 v[12:15], v65, v57, v[12:15]
	v_mfma_f32_16x16x4_f32 v[8:11], v66, v58, v[8:11]
	v_mfma_f32_16x16x4_f32 v[12:15], v67, v59, v[12:15]
	v_mfma_f32_16x16x4_f32 v[8:11], v68, v60, v[8:11]
	v_mfma_f32_16x16x4_f32 v[12:15], v69, v61, v[12:15]
	v_mfma_f32_16x16x4_f32 v[8:11], v70, v62, v[8:11]
	v_mfma_f32_16x16x4_f32 v[12:15], v71, v63, v[12:15]
	global_load_dwordx4 v[20:23], v[4:5], off offset:1088
	ds_read_b128 v[56:59], v148 offset:11264
	ds_read_b128 v[60:63], v148 offset:11280
	s_waitcnt vmcnt(7)
	v_lshlrev_b32_e32 v64, 16, v24
	v_and_b32_e32 v65, 0xffff0000, v24
	v_lshlrev_b32_e32 v66, 16, v25
	v_and_b32_e32 v67, 0xffff0000, v25
	v_lshlrev_b32_e32 v68, 16, v26
	v_and_b32_e32 v69, 0xffff0000, v26
	v_lshlrev_b32_e32 v70, 16, v27
	v_and_b32_e32 v71, 0xffff0000, v27
	s_waitcnt lgkmcnt(2)
	v_mfma_f32_16x16x4_f32 v[8:11], v64, v48, v[8:11]
	v_mfma_f32_16x16x4_f32 v[12:15], v65, v49, v[12:15]
	v_mfma_f32_16x16x4_f32 v[8:11], v66, v50, v[8:11]
	v_mfma_f32_16x16x4_f32 v[12:15], v67, v51, v[12:15]
	v_mfma_f32_16x16x4_f32 v[8:11], v68, v52, v[8:11]
	v_mfma_f32_16x16x4_f32 v[12:15], v69, v53, v[12:15]
	v_mfma_f32_16x16x4_f32 v[8:11], v70, v54, v[8:11]
	v_mfma_f32_16x16x4_f32 v[12:15], v71, v55, v[12:15]
	global_load_dwordx4 v[24:27], v[4:5], off offset:1152
	ds_read_b128 v[48:51], v148 offset:12288
	ds_read_b128 v[52:55], v148 offset:12304
	s_waitcnt vmcnt(7)
	v_lshlrev_b32_e32 v64, 16, v28
	v_and_b32_e32 v65, 0xffff0000, v28
	v_lshlrev_b32_e32 v66, 16, v29
	v_and_b32_e32 v67, 0xffff0000, v29
	v_lshlrev_b32_e32 v68, 16, v30
	v_and_b32_e32 v69, 0xffff0000, v30
	v_lshlrev_b32_e32 v70, 16, v31
	v_and_b32_e32 v71, 0xffff0000, v31
	s_waitcnt lgkmcnt(2)
	v_mfma_f32_16x16x4_f32 v[8:11], v64, v56, v[8:11]
	v_mfma_f32_16x16x4_f32 v[12:15], v65, v57, v[12:15]
	v_mfma_f32_16x16x4_f32 v[8:11], v66, v58, v[8:11]
	v_mfma_f32_16x16x4_f32 v[12:15], v67, v59, v[12:15]
	v_mfma_f32_16x16x4_f32 v[8:11], v68, v60, v[8:11]
	v_mfma_f32_16x16x4_f32 v[12:15], v69, v61, v[12:15]
	v_mfma_f32_16x16x4_f32 v[8:11], v70, v62, v[8:11]
	v_mfma_f32_16x16x4_f32 v[12:15], v71, v63, v[12:15]
	global_load_dwordx4 v[28:31], v[4:5], off offset:1216
	ds_read_b128 v[56:59], v148 offset:13312
	ds_read_b128 v[60:63], v148 offset:13328
	s_waitcnt vmcnt(7)
	v_lshlrev_b32_e32 v64, 16, v32
	v_and_b32_e32 v65, 0xffff0000, v32
	v_lshlrev_b32_e32 v66, 16, v33
	v_and_b32_e32 v67, 0xffff0000, v33
	v_lshlrev_b32_e32 v68, 16, v34
	v_and_b32_e32 v69, 0xffff0000, v34
	v_lshlrev_b32_e32 v70, 16, v35
	v_and_b32_e32 v71, 0xffff0000, v35
	s_waitcnt lgkmcnt(2)
	v_mfma_f32_16x16x4_f32 v[8:11], v64, v48, v[8:11]
	v_mfma_f32_16x16x4_f32 v[12:15], v65, v49, v[12:15]
	v_mfma_f32_16x16x4_f32 v[8:11], v66, v50, v[8:11]
	v_mfma_f32_16x16x4_f32 v[12:15], v67, v51, v[12:15]
	v_mfma_f32_16x16x4_f32 v[8:11], v68, v52, v[8:11]
	v_mfma_f32_16x16x4_f32 v[12:15], v69, v53, v[12:15]
	v_mfma_f32_16x16x4_f32 v[8:11], v70, v54, v[8:11]
	v_mfma_f32_16x16x4_f32 v[12:15], v71, v55, v[12:15]
	global_load_dwordx4 v[32:35], v[4:5], off offset:1280
	ds_read_b128 v[48:51], v148 offset:14336
	ds_read_b128 v[52:55], v148 offset:14352
	s_waitcnt vmcnt(7)
	v_lshlrev_b32_e32 v64, 16, v36
	v_and_b32_e32 v65, 0xffff0000, v36
	v_lshlrev_b32_e32 v66, 16, v37
	v_and_b32_e32 v67, 0xffff0000, v37
	v_lshlrev_b32_e32 v68, 16, v38
	v_and_b32_e32 v69, 0xffff0000, v38
	v_lshlrev_b32_e32 v70, 16, v39
	v_and_b32_e32 v71, 0xffff0000, v39
	s_waitcnt lgkmcnt(2)
	v_mfma_f32_16x16x4_f32 v[8:11], v64, v56, v[8:11]
	v_mfma_f32_16x16x4_f32 v[12:15], v65, v57, v[12:15]
	v_mfma_f32_16x16x4_f32 v[8:11], v66, v58, v[8:11]
	v_mfma_f32_16x16x4_f32 v[12:15], v67, v59, v[12:15]
	v_mfma_f32_16x16x4_f32 v[8:11], v68, v60, v[8:11]
	v_mfma_f32_16x16x4_f32 v[12:15], v69, v61, v[12:15]
	v_mfma_f32_16x16x4_f32 v[8:11], v70, v62, v[8:11]
	v_mfma_f32_16x16x4_f32 v[12:15], v71, v63, v[12:15]
	global_load_dwordx4 v[36:39], v[4:5], off offset:1344
	ds_read_b128 v[56:59], v148 offset:15360
	ds_read_b128 v[60:63], v148 offset:15376
	s_waitcnt vmcnt(7)
	v_lshlrev_b32_e32 v64, 16, v40
	v_and_b32_e32 v65, 0xffff0000, v40
	v_lshlrev_b32_e32 v66, 16, v41
	v_and_b32_e32 v67, 0xffff0000, v41
	v_lshlrev_b32_e32 v68, 16, v42
	v_and_b32_e32 v69, 0xffff0000, v42
	v_lshlrev_b32_e32 v70, 16, v43
	v_and_b32_e32 v71, 0xffff0000, v43
	s_waitcnt lgkmcnt(2)
	v_mfma_f32_16x16x4_f32 v[8:11], v64, v48, v[8:11]
	v_mfma_f32_16x16x4_f32 v[12:15], v65, v49, v[12:15]
	v_mfma_f32_16x16x4_f32 v[8:11], v66, v50, v[8:11]
	v_mfma_f32_16x16x4_f32 v[12:15], v67, v51, v[12:15]
	v_mfma_f32_16x16x4_f32 v[8:11], v68, v52, v[8:11]
	v_mfma_f32_16x16x4_f32 v[12:15], v69, v53, v[12:15]
	v_mfma_f32_16x16x4_f32 v[8:11], v70, v54, v[8:11]
	v_mfma_f32_16x16x4_f32 v[12:15], v71, v55, v[12:15]
	global_load_dwordx4 v[40:43], v[4:5], off offset:1408
	ds_read_b128 v[48:51], v148 offset:16384
	ds_read_b128 v[52:55], v148 offset:16400
	s_waitcnt vmcnt(7)
; __device__ __forceinline__ float bf2f(bfu h) { return __uint_as_float(((unsigned)h) << 16); }
; #define SHX(v, m) shx_((v), (m), lane)
; __device__ void ba_item(const Params& p, int L, int rp) {
;     ...
;       _Pragma("unroll") for (int e = 0; e < 8; ++e) { hf[e] = bf2f((bfu)h0[u][e]); hf[8 + e] = bf2f((bfu)h1[u][e]); }
;       float a[8];
;       _Pragma("unroll") for (int j = 0; j < 8; ++j) {
;         float s = 0.f;
;         _Pragma("unroll") for (int e4 = 0; e4 < 4; ++e4) _Pragma("unroll") for (int e = 0; e < 4; ++e) s += hf[e4 * 4 + e] * wr_[j][e4][e];
;         _Pragma("unroll") for (int o = 32; o >= 1; o >>= 1) s += SHX(s, o);
;         a[j] = s;
;       }
	v_lshlrev_b32_e32 v64, 16, v44
	v_and_b32_e32 v65, 0xffff0000, v44
	v_lshlrev_b32_e32 v66, 16, v45
	v_and_b32_e32 v67, 0xffff0000, v45
	v_lshlrev_b32_e32 v68, 16, v46
	v_and_b32_e32 v69, 0xffff0000, v46
	v_lshlrev_b32_e32 v70, 16, v47
	v_and_b32_e32 v71, 0xffff0000, v47
	s_waitcnt lgkmcnt(2)
	v_mfma_f32_16x16x4_f32 v[8:11], v64, v56, v[8:11]
	v_mfma_f32_16x16x4_f32 v[12:15], v65, v57, v[12:15]
	v_mfma_f32_16x16x4_f32 v[8:11], v66, v58, v[8:11]
	v_mfma_f32_16x16x4_f32 v[12:15], v67, v59, v[12:15]
	v_mfma_f32_16x16x4_f32 v[8:11], v68, v60, v[8:11]
	v_mfma_f32_16x16x4_f32 v[12:15], v69, v61, v[12:15]
	v_mfma_f32_16x16x4_f32 v[8:11], v70, v62, v[8:11]
	v_mfma_f32_16x16x4_f32 v[12:15], v71, v63, v[12:15]
	global_load_dwordx4 v[44:47], v[4:5], off offset:1472
	ds_read_b128 v[56:59], v148 offset:17408
	ds_read_b128 v[60:63], v148 offset:17424
	s_waitcnt vmcnt(7)
	v_lshlrev_b32_e32 v64, 16, v16
	v_and_b32_e32 v65, 0xffff0000, v16
	v_lshlrev_b32_e32 v66, 16, v17
	v_and_b32_e32 v67, 0xffff0000, v17
	v_lshlrev_b32_e32 v68, 16, v18
	v_and_b32_e32 v69, 0xffff0000, v18
	v_lshlrev_b32_e32 v70, 16, v19
	v_and_b32_e32 v71, 0xffff0000, v19
	s_waitcnt lgkmcnt(2)
	v_mfma_f32_16x16x4_f32 v[8:11], v64, v48, v[8:11]
	v_mfma_f32_16x16x4_f32 v[12:15], v65, v49, v[12:15]
	v_mfma_f32_16x16x4_f32 v[8:11], v66, v50, v[8:11]
	v_mfma_f32_16x16x4_f32 v[12:15], v67, v51, v[12:15]
	v_mfma_f32_16x16x4_f32 v[8:11], v68, v52, v[8:11]
	v_mfma_f32_16x16x4_f32 v[12:15], v69, v53, v[12:15]
	v_mfma_f32_16x16x4_f32 v[8:11], v70, v54, v[8:11]
	v_mfma_f32_16x16x4_f32 v[12:15], v71, v55, v[12:15]
	global_load_dwordx4 v[16:19], v[4:5], off offset:1536
	ds_read_b128 v[48:51], v148 offset:18432
	ds_read_b128 v[52:55], v148 offset:18448
	s_waitcnt vmcnt(7)
	v_lshlrev_b32_e32 v64, 16, v20
	v_and_b32_e32 v65, 0xffff0000, v20
	v_lshlrev_b32_e32 v66, 16, v21
	v_and_b32_e32 v67, 0xffff0000, v21
	v_lshlrev_b32_e32 v68, 16, v22
	v_and_b32_e32 v69, 0xffff0000, v22
	v_lshlrev_b32_e32 v70, 16, v23
	v_and_b32_e32 v71, 0xffff0000, v23
	s_waitcnt lgkmcnt(2)
	v_mfma_f32_16x16x4_f32 v[8:11], v64, v56, v[8:11]
	v_mfma_f32_16x16x4_f32 v[12:15], v65, v57, v[12:15]
	v_mfma_f32_16x16x4_f32 v[8:11], v66, v58, v[8:11]
	v_mfma_f32_16x16x4_f32 v[12:15], v67, v59, v[12:15]
	v_mfma_f32_16x16x4_f32 v[8:11], v68, v60, v[8:11]
	v_mfma_f32_16x16x4_f32 v[12:15], v69, v61, v[12:15]
	v_mfma_f32_16x16x4_f32 v[8:11], v70, v62, v[8:11]
	v_mfma_f32_16x16x4_f32 v[12:15], v71, v63, v[12:15]
	global_load_dwordx4 v[20:23], v[4:5], off offset:1600
	ds_read_b128 v[56:59], v148 offset:19456
	ds_read_b128 v[60:63], v148 offset:19472
	s_waitcnt vmcnt(7)
	v_lshlrev_b32_e32 v64, 16, v24
	v_and_b32_e32 v65, 0xffff0000, v24
	v_lshlrev_b32_e32 v66, 16, v25
	v_and_b32_e32 v67, 0xffff0000, v25
	v_lshlrev_b32_e32 v68, 16, v26
	v_and_b32_e32 v69, 0xffff0000, v26
	v_lshlrev_b32_e32 v70, 16, v27
	v_and_b32_e32 v71, 0xffff0000, v27
	s_waitcnt lgkmcnt(2)
	v_mfma_f32_16x16x4_f32 v[8:11], v64, v48, v[8:11]
	v_mfma_f32_16x16x4_f32 v[12:15], v65, v49, v[12:15]
	v_mfma_f32_16x16x4_f32 v[8:11], v66, v50, v[8:11]
	v_mfma_f32_16x16x4_f32 v[12:15], v67, v51, v[12:15]
	v_mfma_f32_16x16x4_f32 v[8:11], v68, v52, v[8:11]
	v_mfma_f32_16x16x4_f32 v[12:15], v69, v53, v[12:15]
	v_mfma_f32_16x16x4_f32 v[8:11], v70, v54, v[8:11]
	v_mfma_f32_16x16x4_f32 v[12:15], v71, v55, v[12:15]
	global_load_dwordx4 v[24:27], v[4:5], off offset:1664
	ds_read_b128 v[48:51], v148 offset:20480
	ds_read_b128 v[52:55], v148 offset:20496
	s_waitcnt vmcnt(7)
	v_lshlrev_b32_e32 v64, 16, v28
	v_and_b32_e32 v65, 0xffff0000, v28
	v_lshlrev_b32_e32 v66, 16, v29
	v_and_b32_e32 v67, 0xffff0000, v29
	v_lshlrev_b32_e32 v68, 16, v30
	v_and_b32_e32 v69, 0xffff0000, v30
	v_lshlrev_b32_e32 v70, 16, v31
	v_and_b32_e32 v71, 0xffff0000, v31
	s_waitcnt lgkmcnt(2)
	v_mfma_f32_16x16x4_f32 v[8:11], v64, v56, v[8:11]
	v_mfma_f32_16x16x4_f32 v[12:15], v65, v57, v[12:15]
	v_mfma_f32_16x16x4_f32 v[8:11], v66, v58, v[8:11]
	v_mfma_f32_16x16x4_f32 v[12:15], v67, v59, v[12:15]
	v_mfma_f32_16x16x4_f32 v[8:11], v68, v60, v[8:11]
	v_mfma_f32_16x16x4_f32 v[12:15], v69, v61, v[12:15]
	v_mfma_f32_16x16x4_f32 v[8:11], v70, v62, v[8:11]
	v_mfma_f32_16x16x4_f32 v[12:15], v71, v63, v[12:15]
	global_load_dwordx4 v[28:31], v[4:5], off offset:1728
	ds_read_b128 v[56:59], v148 offset:21504
	ds_read_b128 v[60:63], v148 offset:21520
	s_waitcnt vmcnt(7)
	v_lshlrev_b32_e32 v64, 16, v32
	v_and_b32_e32 v65, 0xffff0000, v32
	v_lshlrev_b32_e32 v66, 16, v33
	v_and_b32_e32 v67, 0xffff0000, v33
	v_lshlrev_b32_e32 v68, 16, v34
	v_and_b32_e32 v69, 0xffff0000, v34
	v_lshlrev_b32_e32 v70, 16, v35
	v_and_b32_e32 v71, 0xffff0000, v35
	s_waitcnt lgkmcnt(2)
	v_mfma_f32_16x16x4_f32 v[8:11], v64, v48, v[8:11]
	v_mfma_f32_16x16x4_f32 v[12:15], v65, v49, v[12:15]
	v_mfma_f32_16x16x4_f32 v[8:11], v66, v50, v[8:11]
	v_mfma_f32_16x16x4_f32 v[12:15], v67, v51, v[12:15]
	v_mfma_f32_16x16x4_f32 v[8:11], v68, v52, v[8:11]
	v_mfma_f32_16x16x4_f32 v[12:15], v69, v53, v[12:15]
	v_mfma_f32_16x16x4_f32 v[8:11], v70, v54, v[8:11]
	v_mfma_f32_16x16x4_f32 v[12:15], v71, v55, v[12:15]
	global_load_dwordx4 v[32:35], v[4:5], off offset:1792
	ds_read_b128 v[48:51], v148 offset:22528
	ds_read_b128 v[52:55], v148 offset:22544
	s_waitcnt vmcnt(7)
	v_lshlrev_b32_e32 v64, 16, v36
	v_and_b32_e32 v65, 0xffff0000, v36
	v_lshlrev_b32_e32 v66, 16, v37
	v_and_b32_e32 v67, 0xffff0000, v37
	v_lshlrev_b32_e32 v68, 16, v38
	v_and_b32_e32 v69, 0xffff0000, v38
	v_lshlrev_b32_e32 v70, 16, v39
	v_and_b32_e32 v71, 0xffff0000, v39
	s_waitcnt lgkmcnt(2)
; __device__ __forceinline__ float bf2f(bfu h) { return __uint_as_float(((unsigned)h) << 16); }
; #define SHX(v, m) shx_((v), (m), lane)
; __device__ void ba_item(const Params& p, int L, int rp) {
;     ...
;       _Pragma("unroll") for (int e = 0; e < 8; ++e) { hf[e] = bf2f((bfu)h0[u][e]); hf[8 + e] = bf2f((bfu)h1[u][e]); }
;       float a[8];
;       _Pragma("unroll") for (int j = 0; j < 8; ++j) {
;         float s = 0.f;
;         _Pragma("unroll") for (int e4 = 0; e4 < 4; ++e4) _Pragma("unroll") for (int e = 0; e < 4; ++e) s += hf[e4 * 4 + e] * wr_[j][e4][e];
;         _Pragma("unroll") for (int o = 32; o >= 1; o >>= 1) s += SHX(s, o);
;         a[j] = s;
;       }
	v_mfma_f32_16x16x4_f32 v[8:11], v64, v56, v[8:11]
	v_mfma_f32_16x16x4_f32 v[12:15], v65, v57, v[12:15]
	v_mfma_f32_16x16x4_f32 v[8:11], v66, v58, v[8:11]
	v_mfma_f32_16x16x4_f32 v[12:15], v67, v59, v[12:15]
	v_mfma_f32_16x16x4_f32 v[8:11], v68, v60, v[8:11]
	v_mfma_f32_16x16x4_f32 v[12:15], v69, v61, v[12:15]
	v_mfma_f32_16x16x4_f32 v[8:11], v70, v62, v[8:11]
	v_mfma_f32_16x16x4_f32 v[12:15], v71, v63, v[12:15]
	global_load_dwordx4 v[36:39], v[4:5], off offset:1856
	ds_read_b128 v[56:59], v148 offset:23552
	ds_read_b128 v[60:63], v148 offset:23568
	s_waitcnt vmcnt(7)
	v_lshlrev_b32_e32 v64, 16, v40
	v_and_b32_e32 v65, 0xffff0000, v40
	v_lshlrev_b32_e32 v66, 16, v41
	v_and_b32_e32 v67, 0xffff0000, v41
	v_lshlrev_b32_e32 v68, 16, v42
	v_and_b32_e32 v69, 0xffff0000, v42
	v_lshlrev_b32_e32 v70, 16, v43
	v_and_b32_e32 v71, 0xffff0000, v43
	s_waitcnt lgkmcnt(2)
	v_mfma_f32_16x16x4_f32 v[8:11], v64, v48, v[8:11]
	v_mfma_f32_16x16x4_f32 v[12:15], v65, v49, v[12:15]
	v_mfma_f32_16x16x4_f32 v[8:11], v66, v50, v[8:11]
	v_mfma_f32_16x16x4_f32 v[12:15], v67, v51, v[12:15]
	v_mfma_f32_16x16x4_f32 v[8:11], v68, v52, v[8:11]
	v_mfma_f32_16x16x4_f32 v[12:15], v69, v53, v[12:15]
	v_mfma_f32_16x16x4_f32 v[8:11], v70, v54, v[8:11]
	v_mfma_f32_16x16x4_f32 v[12:15], v71, v55, v[12:15]
	global_load_dwordx4 v[40:43], v[4:5], off offset:1920
	ds_read_b128 v[48:51], v148 offset:24576
	ds_read_b128 v[52:55], v148 offset:24592
	s_waitcnt vmcnt(7)
	v_lshlrev_b32_e32 v64, 16, v44
	v_and_b32_e32 v65, 0xffff0000, v44
	v_lshlrev_b32_e32 v66, 16, v45
	v_and_b32_e32 v67, 0xffff0000, v45
	v_lshlrev_b32_e32 v68, 16, v46
	v_and_b32_e32 v69, 0xffff0000, v46
	v_lshlrev_b32_e32 v70, 16, v47
	v_and_b32_e32 v71, 0xffff0000, v47
	s_waitcnt lgkmcnt(2)
	v_mfma_f32_16x16x4_f32 v[8:11], v64, v56, v[8:11]
	v_mfma_f32_16x16x4_f32 v[12:15], v65, v57, v[12:15]
	v_mfma_f32_16x16x4_f32 v[8:11], v66, v58, v[8:11]
	v_mfma_f32_16x16x4_f32 v[12:15], v67, v59, v[12:15]
	v_mfma_f32_16x16x4_f32 v[8:11], v68, v60, v[8:11]
	v_mfma_f32_16x16x4_f32 v[12:15], v69, v61, v[12:15]
	v_mfma_f32_16x16x4_f32 v[8:11], v70, v62, v[8:11]
	v_mfma_f32_16x16x4_f32 v[12:15], v71, v63, v[12:15]
	global_load_dwordx4 v[44:47], v[4:5], off offset:1984
	ds_read_b128 v[56:59], v148 offset:25600
	ds_read_b128 v[60:63], v148 offset:25616
	s_waitcnt vmcnt(7)
	v_lshlrev_b32_e32 v64, 16, v16
	v_and_b32_e32 v65, 0xffff0000, v16
	v_lshlrev_b32_e32 v66, 16, v17
	v_and_b32_e32 v67, 0xffff0000, v17
	v_lshlrev_b32_e32 v68, 16, v18
	v_and_b32_e32 v69, 0xffff0000, v18
	v_lshlrev_b32_e32 v70, 16, v19
	v_and_b32_e32 v71, 0xffff0000, v19
	s_waitcnt lgkmcnt(2)
	v_mfma_f32_16x16x4_f32 v[8:11], v64, v48, v[8:11]
	v_mfma_f32_16x16x4_f32 v[12:15], v65, v49, v[12:15]
	v_mfma_f32_16x16x4_f32 v[8:11], v66, v50, v[8:11]
	v_mfma_f32_16x16x4_f32 v[12:15], v67, v51, v[12:15]
	v_mfma_f32_16x16x4_f32 v[8:11], v68, v52, v[8:11]
	v_mfma_f32_16x16x4_f32 v[12:15], v69, v53, v[12:15]
	v_mfma_f32_16x16x4_f32 v[8:11], v70, v54, v[8:11]
	v_mfma_f32_16x16x4_f32 v[12:15], v71, v55, v[12:15]
	ds_read_b128 v[48:51], v148 offset:26624
	ds_read_b128 v[52:55], v148 offset:26640
	s_waitcnt vmcnt(6)
	v_lshlrev_b32_e32 v64, 16, v20
	v_and_b32_e32 v65, 0xffff0000, v20
	v_lshlrev_b32_e32 v66, 16, v21
	v_and_b32_e32 v67, 0xffff0000, v21
	v_lshlrev_b32_e32 v68, 16, v22
	v_and_b32_e32 v69, 0xffff0000, v22
	v_lshlrev_b32_e32 v70, 16, v23
	v_and_b32_e32 v71, 0xffff0000, v23
	s_waitcnt lgkmcnt(2)
	v_mfma_f32_16x16x4_f32 v[8:11], v64, v56, v[8:11]
	v_mfma_f32_16x16x4_f32 v[12:15], v65, v57, v[12:15]
	v_mfma_f32_16x16x4_f32 v[8:11], v66, v58, v[8:11]
	v_mfma_f32_16x16x4_f32 v[12:15], v67, v59, v[12:15]
	v_mfma_f32_16x16x4_f32 v[8:11], v68, v60, v[8:11]
	v_mfma_f32_16x16x4_f32 v[12:15], v69, v61, v[12:15]
	v_mfma_f32_16x16x4_f32 v[8:11], v70, v62, v[8:11]
	v_mfma_f32_16x16x4_f32 v[12:15], v71, v63, v[12:15]
	ds_read_b128 v[56:59], v148 offset:27648
	ds_read_b128 v[60:63], v148 offset:27664
	s_waitcnt vmcnt(5)
	v_lshlrev_b32_e32 v64, 16, v24
	v_and_b32_e32 v65, 0xffff0000, v24
	v_lshlrev_b32_e32 v66, 16, v25
	v_and_b32_e32 v67, 0xffff0000, v25
	v_lshlrev_b32_e32 v68, 16, v26
	v_and_b32_e32 v69, 0xffff0000, v26
	v_lshlrev_b32_e32 v70, 16, v27
	v_and_b32_e32 v71, 0xffff0000, v27
	s_waitcnt lgkmcnt(2)
	v_mfma_f32_16x16x4_f32 v[8:11], v64, v48, v[8:11]
	v_mfma_f32_16x16x4_f32 v[12:15], v65, v49, v[12:15]
	v_mfma_f32_16x16x4_f32 v[8:11], v66, v50, v[8:11]
	v_mfma_f32_16x16x4_f32 v[12:15], v67, v51, v[12:15]
	v_mfma_f32_16x16x4_f32 v[8:11], v68, v52, v[8:11]
	v_mfma_f32_16x16x4_f32 v[12:15], v69, v53, v[12:15]
	v_mfma_f32_16x16x4_f32 v[8:11], v70, v54, v[8:11]
	v_mfma_f32_16x16x4_f32 v[12:15], v71, v55, v[12:15]
	ds_read_b128 v[48:51], v148 offset:28672
	ds_read_b128 v[52:55], v148 offset:28688
	s_waitcnt vmcnt(4)
	v_lshlrev_b32_e32 v64, 16, v28
	v_and_b32_e32 v65, 0xffff0000, v28
	v_lshlrev_b32_e32 v66, 16, v29
	v_and_b32_e32 v67, 0xffff0000, v29
	v_lshlrev_b32_e32 v68, 16, v30
	v_and_b32_e32 v69, 0xffff0000, v30
	v_lshlrev_b32_e32 v70, 16, v31
	v_and_b32_e32 v71, 0xffff0000, v31
	s_waitcnt lgkmcnt(2)
	v_mfma_f32_16x16x4_f32 v[8:11], v64, v56, v[8:11]
	v_mfma_f32_16x16x4_f32 v[12:15], v65, v57, v[12:15]
	v_mfma_f32_16x16x4_f32 v[8:11], v66, v58, v[8:11]
	v_mfma_f32_16x16x4_f32 v[12:15], v67, v59, v[12:15]
	v_mfma_f32_16x16x4_f32 v[8:11], v68, v60, v[8:11]
	v_mfma_f32_16x16x4_f32 v[12:15], v69, v61, v[12:15]
	v_mfma_f32_16x16x4_f32 v[8:11], v70, v62, v[8:11]
	v_mfma_f32_16x16x4_f32 v[12:15], v71, v63, v[12:15]
	ds_read_b128 v[56:59], v148 offset:29696
	ds_read_b128 v[60:63], v148 offset:29712
	s_waitcnt vmcnt(3)
; __device__ __forceinline__ float bf2f(bfu h) { return __uint_as_float(((unsigned)h) << 16); }
; #define SHX(v, m) shx_((v), (m), lane)
; __device__ void ba_item(const Params& p, int L, int rp) {
;     ...
;       _Pragma("unroll") for (int e = 0; e < 8; ++e) { hf[e] = bf2f((bfu)h0[u][e]); hf[8 + e] = bf2f((bfu)h1[u][e]); }
;       float a[8];
;       _Pragma("unroll") for (int j = 0; j < 8; ++j) {
;         float s = 0.f;
;         _Pragma("unroll") for (int e4 = 0; e4 < 4; ++e4) _Pragma("unroll") for (int e = 0; e < 4; ++e) s += hf[e4 * 4 + e] * wr_[j][e4][e];
;         _Pragma("unroll") for (int o = 32; o >= 1; o >>= 1) s += SHX(s, o);
;         a[j] = s;
;       }
	v_lshlrev_b32_e32 v64, 16, v32
	v_and_b32_e32 v65, 0xffff0000, v32
	v_lshlrev_b32_e32 v66, 16, v33
	v_and_b32_e32 v67, 0xffff0000, v33
	v_lshlrev_b32_e32 v68, 16, v34
	v_and_b32_e32 v69, 0xffff0000, v34
	v_lshlrev_b32_e32 v70, 16, v35
	v_and_b32_e32 v71, 0xffff0000, v35
	s_waitcnt lgkmcnt(2)
	v_mfma_f32_16x16x4_f32 v[8:11], v64, v48, v[8:11]
	v_mfma_f32_16x16x4_f32 v[12:15], v65, v49, v[12:15]
	v_mfma_f32_16x16x4_f32 v[8:11], v66, v50, v[8:11]
	v_mfma_f32_16x16x4_f32 v[12:15], v67, v51, v[12:15]
	v_mfma_f32_16x16x4_f32 v[8:11], v68, v52, v[8:11]
	v_mfma_f32_16x16x4_f32 v[12:15], v69, v53, v[12:15]
	v_mfma_f32_16x16x4_f32 v[8:11], v70, v54, v[8:11]
	v_mfma_f32_16x16x4_f32 v[12:15], v71, v55, v[12:15]
	ds_read_b128 v[48:51], v148 offset:30720
	ds_read_b128 v[52:55], v148 offset:30736
	s_waitcnt vmcnt(2)
	v_lshlrev_b32_e32 v64, 16, v36
	v_and_b32_e32 v65, 0xffff0000, v36
	v_lshlrev_b32_e32 v66, 16, v37
	v_and_b32_e32 v67, 0xffff0000, v37
	v_lshlrev_b32_e32 v68, 16, v38
	v_and_b32_e32 v69, 0xffff0000, v38
	v_lshlrev_b32_e32 v70, 16, v39
	v_and_b32_e32 v71, 0xffff0000, v39
	s_waitcnt lgkmcnt(2)
	v_mfma_f32_16x16x4_f32 v[8:11], v64, v56, v[8:11]
	v_mfma_f32_16x16x4_f32 v[12:15], v65, v57, v[12:15]
	v_mfma_f32_16x16x4_f32 v[8:11], v66, v58, v[8:11]
	v_mfma_f32_16x16x4_f32 v[12:15], v67, v59, v[12:15]
	v_mfma_f32_16x16x4_f32 v[8:11], v68, v60, v[8:11]
	v_mfma_f32_16x16x4_f32 v[12:15], v69, v61, v[12:15]
	v_mfma_f32_16x16x4_f32 v[8:11], v70, v62, v[8:11]
	v_mfma_f32_16x16x4_f32 v[12:15], v71, v63, v[12:15]
	ds_read_b128 v[56:59], v148 offset:31744
	ds_read_b128 v[60:63], v148 offset:31760
	s_waitcnt vmcnt(1)
	v_lshlrev_b32_e32 v64, 16, v40
	v_and_b32_e32 v65, 0xffff0000, v40
	v_lshlrev_b32_e32 v66, 16, v41
	v_and_b32_e32 v67, 0xffff0000, v41
	v_lshlrev_b32_e32 v68, 16, v42
	v_and_b32_e32 v69, 0xffff0000, v42
	v_lshlrev_b32_e32 v70, 16, v43
	v_and_b32_e32 v71, 0xffff0000, v43
	s_waitcnt lgkmcnt(2)
	v_mfma_f32_16x16x4_f32 v[8:11], v64, v48, v[8:11]
	v_mfma_f32_16x16x4_f32 v[12:15], v65, v49, v[12:15]
	v_mfma_f32_16x16x4_f32 v[8:11], v66, v50, v[8:11]
	v_mfma_f32_16x16x4_f32 v[12:15], v67, v51, v[12:15]
	v_mfma_f32_16x16x4_f32 v[8:11], v68, v52, v[8:11]
	v_mfma_f32_16x16x4_f32 v[12:15], v69, v53, v[12:15]
	v_mfma_f32_16x16x4_f32 v[8:11], v70, v54, v[8:11]
	v_mfma_f32_16x16x4_f32 v[12:15], v71, v55, v[12:15]
	s_waitcnt vmcnt(0)
	v_lshlrev_b32_e32 v64, 16, v44
	v_and_b32_e32 v65, 0xffff0000, v44
	v_lshlrev_b32_e32 v66, 16, v45
	v_and_b32_e32 v67, 0xffff0000, v45
	v_lshlrev_b32_e32 v68, 16, v46
	v_and_b32_e32 v69, 0xffff0000, v46
	v_lshlrev_b32_e32 v70, 16, v47
	v_and_b32_e32 v71, 0xffff0000, v47
	s_waitcnt lgkmcnt(0)
; __device__ __forceinline__ float fexp(float x) { return __builtin_amdgcn_exp2f(x * 1.4426950408889634f); }
; __device__ __forceinline__ float flog(float x) { return __builtin_amdgcn_logf(x) * 0.6931471805599453f; }
; __device__ __forceinline__ float frsq(float x) { return __builtin_amdgcn_rsqf(x); }
; __device__ __forceinline__ float sigmoidf_(float x) { return frcp(1.0f + fexp(-x)); }
; __device__ void ba_item(const Params& p, int L, int rp) {
;     ...
;       if (lane < 8) {
;         float s16 = 0.f;
;         _Pragma("unroll") for (int i = 0; i < 4; ++i) s16 += (ps[u][i][0] + ps[u][i][1]) + (ps[u][i][2] + ps[u][i][3]);
;         float rs = frsq(s16 * (1.0f / 1024.0f) + 1e-6f);
;         float v = 0.f;
;         _Pragma("unroll") for (int j = 0; j < 8; ++j) if (lane == j) v = a[j];
;         v *= rs;
;         float r;
;         if (lane < 4) r = sigmoidf_(v);
;         else {
;           int hh = lane - 4;
;           float z = v + p.dn_dt_bias[(L >> 1) * 4 + hh];
;           float sp = (z > 20.f) ? z : flog(1.0f + fexp(z));
;           r = -fexp(p.dn_a_log[(L >> 1) * 4 + hh]) * sp;
;         }
;         miscw[MF_BG + (long)row * 8 + lane] = r;
	v_mfma_f32_16x16x4_f32 v[8:11], v64, v56, v[8:11]
	v_mfma_f32_16x16x4_f32 v[12:15], v65, v57, v[12:15]
	v_mfma_f32_16x16x4_f32 v[8:11], v66, v58, v[8:11]
	v_mfma_f32_16x16x4_f32 v[12:15], v67, v59, v[12:15]
	v_mfma_f32_16x16x4_f32 v[8:11], v68, v60, v[8:11]
	v_mfma_f32_16x16x4_f32 v[12:15], v69, v61, v[12:15]
	v_mfma_f32_16x16x4_f32 v[8:11], v70, v62, v[8:11]
	v_mfma_f32_16x16x4_f32 v[12:15], v71, v63, v[12:15]
	v_cmp_gt_u32_e32 vcc, 8, v2
	s_and_saveexec_b64 s[12:13], vcc
	s_nop 4
	v_add_f32_e32 v72, v72, v73
	v_add_f32_e32 v74, v74, v75
	v_add_f32_e32 v72, v72, v74
	v_add_f32_e32 v76, v76, v77
	v_add_f32_e32 v78, v78, v79
	v_add_f32_e32 v76, v76, v78
	v_add_f32_e32 v80, v80, v81
	v_add_f32_e32 v82, v82, v83
	v_add_f32_e32 v80, v80, v82
	v_add_f32_e32 v84, v84, v85
	v_add_f32_e32 v86, v86, v87
	v_add_f32_e32 v84, v84, v86
	v_add_f32_e32 v72, 0, v72
	v_add_f32_e32 v72, v76, v72
	v_add_f32_e32 v72, v80, v72
	v_add_f32_e32 v72, v84, v72
	v_fmamk_f32 v72, v72, 0x3a800000, v201
	v_rsq_f32_e32 v72, v72
	s_nop 0
	v_add_f32_e32 v8, v8, v12
	v_mul_f32_e32 v144, v8, v72
	v_mul_f32_e32 v145, 0xbfb8aa3b, v144
	v_exp_f32_e32 v145, v145
	s_nop 0
	v_add_f32_e32 v145, 1.0, v145
	v_rcp_f32_e32 v145, v145
	v_add_f32_e32 v146, v144, v142
	v_mul_f32_e32 v147, 0x3fb8aa3b, v146
	v_exp_f32_e32 v147, v147
	v_cmp_lt_f32_e64 s[0:1], s57, v146
	v_add_f32_e32 v147, 1.0, v147
	v_log_f32_e32 v147, v147
	s_nop 0
	v_mul_f32_e32 v147, 0x3f317218, v147
	v_cndmask_b32_e64 v146, v147, v146, s[0:1]
	v_mul_f32_e32 v147, 0x3fb8aa3b, v143
	v_exp_f32_e32 v147, v147
	s_nop 0
	v_mul_f32_e64 v146, v146, -v147
	v_cmp_gt_u32_e64 s[0:1], 4, v138
	s_nop 1
	v_cndmask_b32_e64 v146, v146, v145, s[0:1]
	global_store_dword v[140:141], v146, off offset:0
	v_add_f32_e32 v88, v88, v89
	v_add_f32_e32 v90, v90, v91
	v_add_f32_e32 v88, v88, v90
	v_add_f32_e32 v92, v92, v93
	v_add_f32_e32 v94, v94, v95
	v_add_f32_e32 v92, v92, v94
	v_add_f32_e32 v96, v96, v97
	v_add_f32_e32 v98, v98, v99
	v_add_f32_e32 v96, v96, v98
	v_add_f32_e32 v100, v100, v101
	v_add_f32_e32 v102, v102, v103
	v_add_f32_e32 v100, v100, v102
	v_add_f32_e32 v88, 0, v88
	v_add_f32_e32 v88, v92, v88
	v_add_f32_e32 v88, v96, v88
	v_add_f32_e32 v88, v100, v88
	v_fmamk_f32 v88, v88, 0x3a800000, v201
	v_rsq_f32_e32 v88, v88
	s_nop 0
	v_add_f32_e32 v9, v9, v13
	v_mul_f32_e32 v144, v9, v88
	v_mul_f32_e32 v145, 0xbfb8aa3b, v144
	v_exp_f32_e32 v145, v145
	s_nop 0
	v_add_f32_e32 v145, 1.0, v145
	v_rcp_f32_e32 v145, v145
	v_add_f32_e32 v146, v144, v142
	v_mul_f32_e32 v147, 0x3fb8aa3b, v146
	v_exp_f32_e32 v147, v147
	v_cmp_lt_f32_e64 s[0:1], s57, v146
	v_add_f32_e32 v147, 1.0, v147
	v_log_f32_e32 v147, v147
	s_nop 0
	v_mul_f32_e32 v147, 0x3f317218, v147
	v_cndmask_b32_e64 v146, v147, v146, s[0:1]
	v_mul_f32_e32 v147, 0x3fb8aa3b, v143
	v_exp_f32_e32 v147, v147
	s_nop 0
	v_mul_f32_e64 v146, v146, -v147
	v_cmp_gt_u32_e64 s[0:1], 4, v138
	s_nop 1
	v_cndmask_b32_e64 v146, v146, v145, s[0:1]
	global_store_dword v[140:141], v146, off offset:32
	v_add_f32_e32 v104, v104, v105
	v_add_f32_e32 v106, v106, v107
	v_add_f32_e32 v104, v104, v106
	v_add_f32_e32 v108, v108, v109
	v_add_f32_e32 v110, v110, v111
	v_add_f32_e32 v108, v108, v110
	v_add_f32_e32 v112, v112, v113
	v_add_f32_e32 v114, v114, v115
	v_add_f32_e32 v112, v112, v114
	v_add_f32_e32 v116, v116, v117
	v_add_f32_e32 v118, v118, v119
	v_add_f32_e32 v116, v116, v118
	v_add_f32_e32 v104, 0, v104
	v_add_f32_e32 v104, v108, v104
	v_add_f32_e32 v104, v112, v104
	v_add_f32_e32 v104, v116, v104
	v_fmamk_f32 v104, v104, 0x3a800000, v201
	v_rsq_f32_e32 v104, v104
	s_nop 0
	v_add_f32_e32 v10, v10, v14
	v_mul_f32_e32 v144, v10, v104
	v_mul_f32_e32 v145, 0xbfb8aa3b, v144
	v_exp_f32_e32 v145, v145
	s_nop 0
	v_add_f32_e32 v145, 1.0, v145
	v_rcp_f32_e32 v145, v145
	v_add_f32_e32 v146, v144, v142
	v_mul_f32_e32 v147, 0x3fb8aa3b, v146
	v_exp_f32_e32 v147, v147
	v_cmp_lt_f32_e64 s[0:1], s57, v146
	v_add_f32_e32 v147, 1.0, v147
	v_log_f32_e32 v147, v147
	s_nop 0
	v_mul_f32_e32 v147, 0x3f317218, v147
	v_cndmask_b32_e64 v146, v147, v146, s[0:1]
	v_mul_f32_e32 v147, 0x3fb8aa3b, v143
	v_exp_f32_e32 v147, v147
	s_nop 0
	v_mul_f32_e64 v146, v146, -v147
	v_cmp_gt_u32_e64 s[0:1], 4, v138
	s_nop 1
	v_cndmask_b32_e64 v146, v146, v145, s[0:1]
	global_store_dword v[140:141], v146, off offset:64
	v_add_f32_e32 v120, v120, v121
	v_add_f32_e32 v122, v122, v123
	v_add_f32_e32 v120, v120, v122
	v_add_f32_e32 v124, v124, v125
	v_add_f32_e32 v126, v126, v127
	v_add_f32_e32 v124, v124, v126
	v_add_f32_e32 v128, v128, v129
	v_add_f32_e32 v130, v130, v131
	v_add_f32_e32 v128, v128, v130
	v_add_f32_e32 v132, v132, v133
	v_add_f32_e32 v134, v134, v135
	v_add_f32_e32 v132, v132, v134
	v_add_f32_e32 v120, 0, v120
	v_add_f32_e32 v120, v124, v120
	v_add_f32_e32 v120, v128, v120
	v_add_f32_e32 v120, v132, v120
	v_fmamk_f32 v120, v120, 0x3a800000, v201
	v_rsq_f32_e32 v120, v120
	s_nop 0
	v_add_f32_e32 v11, v11, v15
	v_mul_f32_e32 v144, v11, v120
	v_mul_f32_e32 v145, 0xbfb8aa3b, v144
	v_exp_f32_e32 v145, v145
	s_nop 0
	v_add_f32_e32 v145, 1.0, v145
	v_rcp_f32_e32 v145, v145
	v_add_f32_e32 v146, v144, v142
	v_mul_f32_e32 v147, 0x3fb8aa3b, v146
	v_exp_f32_e32 v147, v147
	v_cmp_lt_f32_e64 s[0:1], s57, v146
	v_add_f32_e32 v147, 1.0, v147
	v_log_f32_e32 v147, v147
	s_nop 0
	v_mul_f32_e32 v147, 0x3f317218, v147
	v_cndmask_b32_e64 v146, v147, v146, s[0:1]
	v_mul_f32_e32 v147, 0x3fb8aa3b, v143
	v_exp_f32_e32 v147, v147
	s_nop 0
	v_mul_f32_e64 v146, v146, -v147
	v_cmp_gt_u32_e64 s[0:1], 4, v138
	s_nop 1
	v_cndmask_b32_e64 v146, v146, v145, s[0:1]
	global_store_dword v[140:141], v146, off offset:96
	s_or_b64 exec, exec, s[12:13]
	s_barrier
	s_branch .LBB0_627
